# FoX bias tile: 8 LDS reads issued together with progressive lgkmcnt waits (was 4 dependent read/wait groups)
# speedup vs baseline: 1.0032x; 1.0032x over previous
; #define LAS __attribute__((address_space(3)))
; template <int MODE> DI void attn_h1(AttnCtx& c, const bf16x8 (&q)[8], f32x16 (&o)[4], f32x16& s0, f32x16& s1, ldsp lds, int kbuf, int bbuf, int tj, int lane) {
;     ...
;             if (MODE == MD_FOX) {
;                 const LAS float* bl = (const LAS float*)(lds + A_BIAS + bbuf);
;                 const int kbase = tj * 64 + 4 * h;
;                 const bool needmask = tj >= c.whi;
; #pragma unroll
;                 for (int g4 = 0; g4 < 4; ++g4) {
;                     const f32x4 b0 = *(const LAS f32x4*)(bl + 8 * g4 + 4 * h), b1 = *(const LAS f32x4*)(bl + 32 + 8 * g4 + 4 * h);
; #pragma unroll
;                     for (int e = 0; e < 4; ++e) { s0[4 * g4 + e] += b0[e]; s1[4 * g4 + e] += b1[e]; }
;                 }
.LBB0_564:
	s_or_b64 exec, exec, s[4:5]
	v_cmp_le_i32_e32 vcc, s95, v242
	s_and_b32 s21, s96, 1
	s_and_b64 s[22:23], vcc, s[2:3]
	s_and_saveexec_b64 s[24:25], s[22:23]
	s_cbranch_execz .LBB0_569
	s_mul_i32 s2, s21, 0x4400
	v_add_u32_e32 v0, s2, v237
	ds_read_b128 v[98:101], v0 offset:8704
	ds_read_b128 v[82:85], v0
	ds_read_b128 v[178:181], v0 offset:32
	ds_read_b128 v[182:185], v0 offset:8736
	ds_read_b128 v[206:209], v0 offset:64
	ds_read_b128 v[210:213], v0 offset:8768
	ds_read_b128 v[214:217], v0 offset:96
	ds_read_b128 v[218:221], v0 offset:8800
	v_cmp_ge_i32_e32 vcc, s95, v242
	s_waitcnt lgkmcnt(6)
	v_mfma_f32_32x32x16_bf16 v[98:113], v[98:101], v[136:139], 0
	v_mfma_f32_32x32x16_bf16 v[82:97], v[82:85], v[136:139], 0
	s_waitcnt lgkmcnt(4)
	v_mfma_f32_32x32x16_bf16 v[82:97], v[178:181], v[140:143], v[82:97]
	v_mfma_f32_32x32x16_bf16 v[98:113], v[182:185], v[140:143], v[98:113]
	ds_read_b128 v[178:181], v0 offset:128
	ds_read_b128 v[182:185], v0 offset:8832
	s_waitcnt lgkmcnt(4)
	v_mfma_f32_32x32x16_bf16 v[82:97], v[206:209], v[144:147], v[82:97]
	v_mfma_f32_32x32x16_bf16 v[98:113], v[210:213], v[144:147], v[98:113]
	ds_read_b128 v[206:209], v0 offset:160
	ds_read_b128 v[210:213], v0 offset:8864
	s_waitcnt lgkmcnt(4)
	v_mfma_f32_32x32x16_bf16 v[82:97], v[214:217], v[148:151], v[82:97]
	v_mfma_f32_32x32x16_bf16 v[98:113], v[218:221], v[148:151], v[98:113]
	ds_read_b128 v[214:217], v0 offset:192
	ds_read_b128 v[218:221], v0 offset:8896
	s_waitcnt lgkmcnt(4)
	v_mfma_f32_32x32x16_bf16 v[82:97], v[178:181], v[152:155], v[82:97]
	v_mfma_f32_32x32x16_bf16 v[98:113], v[182:185], v[152:155], v[98:113]
	ds_read_b128 v[178:181], v0 offset:224
	ds_read_b128 v[182:185], v0 offset:8928
	v_lshl_add_u32 v0, s21, 8, v243
	s_waitcnt lgkmcnt(4)
	v_mfma_f32_32x32x16_bf16 v[82:97], v[206:209], v[156:159], v[82:97]
	v_mfma_f32_32x32x16_bf16 v[98:113], v[210:213], v[156:159], v[98:113]
	s_waitcnt lgkmcnt(2)
	v_mfma_f32_32x32x16_bf16 v[82:97], v[214:217], v[160:163], v[82:97]
	v_mfma_f32_32x32x16_bf16 v[98:113], v[218:221], v[160:163], v[98:113]
	s_waitcnt lgkmcnt(0)
	v_mfma_f32_32x32x16_bf16 v[82:97], v[178:181], v[164:167], v[82:97]
	v_mfma_f32_32x32x16_bf16 v[98:113], v[182:185], v[164:167], v[98:113]
	ds_read_b128 v[178:181], v0
	ds_read_b128 v[182:185], v0 offset:32
	ds_read_b128 v[206:209], v0 offset:64
	ds_read_b128 v[210:213], v0 offset:96
	ds_read_b128 v[202:205], v0 offset:128
	ds_read_b128 v[214:217], v0 offset:160
	ds_read_b128 v[218:221], v0 offset:192
	ds_read_b128 v[222:225], v0 offset:224
	s_waitcnt lgkmcnt(7)
	s_nop 2
	v_add_f32_e32 v82, v82, v178
	v_add_f32_e32 v83, v83, v179
	v_add_f32_e32 v84, v84, v180
	v_add_f32_e32 v85, v85, v181
	s_waitcnt lgkmcnt(6)
	v_add_f32_e32 v86, v86, v182
	v_add_f32_e32 v87, v87, v183
	v_add_f32_e32 v88, v88, v184
	v_add_f32_e32 v89, v89, v185
	s_waitcnt lgkmcnt(5)
	v_add_f32_e32 v90, v90, v206
	v_add_f32_e32 v91, v91, v207
	v_add_f32_e32 v92, v92, v208
	v_add_f32_e32 v93, v93, v209
	s_waitcnt lgkmcnt(4)
	v_add_f32_e32 v94, v94, v210
	v_add_f32_e32 v95, v95, v211
	v_add_f32_e32 v96, v96, v212
	v_add_f32_e32 v97, v97, v213
	s_waitcnt lgkmcnt(3)
	v_add_f32_e32 v98, v98, v202
	v_add_f32_e32 v99, v99, v203
	v_add_f32_e32 v100, v100, v204
	v_add_f32_e32 v101, v101, v205
	s_waitcnt lgkmcnt(2)
	v_add_f32_e32 v102, v102, v214
	v_add_f32_e32 v103, v103, v215
	v_add_f32_e32 v104, v104, v216
	v_add_f32_e32 v105, v105, v217
	s_waitcnt lgkmcnt(1)
	v_add_f32_e32 v106, v106, v218
	v_add_f32_e32 v107, v107, v219
	v_add_f32_e32 v108, v108, v220
	v_add_f32_e32 v109, v109, v221
	s_waitcnt lgkmcnt(0)
	v_add_f32_e32 v110, v110, v222
	v_add_f32_e32 v111, v111, v223
	v_add_f32_e32 v112, v112, v224
	v_add_f32_e32 v113, v113, v225
	s_and_saveexec_b64 s[26:27], vcc
	s_cbranch_execz .LBB0_567
; template <int MODE> DI void attn_h1(AttnCtx& c, const bf16x8 (&q)[8], f32x16 (&o)[4], f32x16& s0, f32x16& s1, ldsp lds, int kbuf, int bbuf, int tj, int lane) {
;     ...
;                 if (needmask) {
; #pragma unroll
;                     for (int e = 0; e < 16; ++e) {
;                         const int k0 = kbase + 8 * (e >> 2) + (e & 3);
;                         s0[e] = (k0 <= c.t) ? s0[e] : NINF; s1[e] = (k0 + 32 <= c.t) ? s1[e] : NINF;
;                     }
;                 }
	v_or_b32_e32 v0, 3, v244
	v_cmp_le_i32_e32 vcc, v0, v115
	v_or_b32_e32 v0, 2, v244
	v_cmp_le_i32_e64 s[2:3], v0, v196
	v_or_b32_e32 v0, 9, v244
	v_cmp_le_i32_e64 s[4:5], v0, v115
	v_or_b32_e32 v0, 8, v244
	v_cmp_le_i32_e64 s[6:7], v0, v196
	v_or_b32_e32 v0, 11, v244
	v_cmp_le_i32_e64 s[8:9], v0, v115
	v_or_b32_e32 v0, 10, v244
	v_cmp_le_i32_e64 s[10:11], v0, v196
	v_or_b32_e32 v0, 17, v244
	v_cmp_le_i32_e64 s[12:13], v0, v115
	v_or_b32_e32 v0, 16, v244
	v_cmp_le_i32_e64 s[14:15], v0, v196
	v_or_b32_e32 v0, 19, v244
	v_cmp_le_i32_e64 s[48:49], v0, v115
	v_or_b32_e32 v0, 18, v244
	v_cmp_le_i32_e64 s[50:51], v0, v196
	v_or_b32_e32 v0, 25, v244
	v_cmp_le_i32_e64 s[52:53], v0, v115
	v_or_b32_e32 v0, 24, v244
	v_cmp_le_i32_e64 s[54:55], v0, v196
	v_or_b32_e32 v0, 27, v244
	v_cmp_le_i32_e64 s[56:57], v0, v115
	v_or_b32_e32 v0, 26, v244
	v_cmp_le_i32_e64 s[58:59], v0, v196
	v_or_b32_e32 v0, 59, v244
	v_cmp_le_i32_e64 s[60:61], v0, v33
	v_or_b32_e32 v0, 58, v244
	v_cmp_le_i32_e64 s[62:63], v0, v114
	v_or_b32_e32 v0, 57, v244
	v_cmp_le_i32_e64 s[64:65], v0, v15
	v_or_b32_e32 v0, 56, v244
	v_cmp_le_i32_e64 s[66:67], v0, v14
	v_or_b32_e32 v0, 51, v244
	v_cmp_le_i32_e64 s[68:69], v0, v13
	v_or_b32_e32 v0, 50, v244
	v_cmp_le_i32_e64 s[70:71], v0, v12
	v_or_b32_e32 v0, 49, v244
	v_cmp_le_i32_e64 s[72:73], v0, v11
	v_or_b32_e32 v0, 48, v244
	v_cmp_le_i32_e64 s[74:75], v0, v10
	v_or_b32_e32 v0, 43, v244
	v_cmp_le_i32_e64 s[76:77], v0, v9
	v_or_b32_e32 v0, 42, v244
	v_cmp_le_i32_e64 s[78:79], v0, v8
	v_or_b32_e32 v0, 41, v244
	v_cmp_le_i32_e64 s[80:81], v0, v7
	v_or_b32_e32 v0, 40, v244
	v_cmp_le_i32_e64 s[82:83], v0, v6
	v_or_b32_e32 v0, 35, v244
	v_cmp_le_i32_e64 s[84:85], v0, v5
	v_or_b32_e32 v0, 34, v244
	v_cmp_le_i32_e64 s[86:87], v0, v4
	v_or_b32_e32 v0, 33, v244
	v_cmp_le_i32_e64 s[88:89], v0, v3
	v_or_b32_e32 v0, 32, v244
	v_cmp_le_i32_e64 s[92:93], v244, v196
	v_cmp_le_i32_e64 s[90:91], v0, v2
	v_cndmask_b32_e64 v103, v230, v103, s[80:81]
	v_cndmask_b32_e64 v82, v230, v82, s[92:93]
	v_cmp_lt_i32_e64 s[92:93], v244, v196
	v_readlane_b32 s80, v254, 38
	v_cndmask_b32_e32 v85, v230, v85, vcc
	v_cndmask_b32_e64 v83, v230, v83, s[92:93]
	v_cndmask_b32_e64 v84, v230, v84, s[2:3]
	v_cndmask_b32_e64 v87, v230, v87, s[4:5]
	v_cndmask_b32_e64 v86, v230, v86, s[6:7]
	v_cndmask_b32_e64 v89, v230, v89, s[8:9]
	v_cndmask_b32_e64 v88, v230, v88, s[10:11]
	v_cndmask_b32_e64 v91, v230, v91, s[12:13]
	v_cndmask_b32_e64 v90, v230, v90, s[14:15]
	v_cndmask_b32_e64 v93, v230, v93, s[48:49]
	v_cndmask_b32_e64 v92, v230, v92, s[50:51]
	v_cndmask_b32_e64 v95, v230, v95, s[52:53]
	s_mov_b32 s53, 0xff800000
	s_mov_b32 s52, 0x800000
	v_cndmask_b32_e64 v94, v230, v94, s[54:55]
	v_cndmask_b32_e64 v97, v230, v97, s[56:57]
	v_cndmask_b32_e64 v96, v230, v96, s[58:59]
	v_cndmask_b32_e64 v113, v230, v113, s[60:61]
	v_cndmask_b32_e64 v112, v230, v112, s[62:63]
	v_cndmask_b32_e64 v111, v230, v111, s[64:65]
	v_cndmask_b32_e64 v110, v230, v110, s[66:67]
	v_cndmask_b32_e64 v109, v230, v109, s[68:69]
	v_cndmask_b32_e64 v108, v230, v108, s[70:71]
	v_cndmask_b32_e64 v107, v230, v107, s[72:73]
	v_cndmask_b32_e64 v106, v230, v106, s[74:75]
	v_cndmask_b32_e64 v105, v230, v105, s[76:77]
	v_cndmask_b32_e64 v104, v230, v104, s[78:79]
	v_cndmask_b32_e64 v102, v230, v102, s[82:83]
	v_cndmask_b32_e64 v101, v230, v101, s[84:85]
	v_cndmask_b32_e64 v100, v230, v100, s[86:87]
	v_cndmask_b32_e64 v99, v230, v99, s[88:89]
	v_readlane_b32 s81, v254, 39
	v_cndmask_b32_e64 v98, v230, v98, s[90:91]
